# v13 + GU SwiGLU epilogue rewritten: q=G*U, t=G*rs*(-log2e), pk_fma (1+e)/rs^2, rcp, out=q*r (40 VALU per row group instead of 52, same f32 math)
# baseline (speedup 1.0000x reference)
.Lgu_rs_done:
	v_readlane_b32 s4, v254, 32
	v_readlane_b32 s5, v254, 33
	v_mul_f32_e32 v134, 0xbfb8aa3b, v194
	v_mul_f32_e32 v135, v194, v194
	v_rcp_f32_e32 v135, v135
	v_pk_mul_f32 v[122:123], v[122:123], v[126:127]
	v_pk_mul_f32 v[124:125], v[124:125], v[128:129]
	v_pk_mul_f32 v[114:115], v[114:115], v[118:119]
	v_pk_mul_f32 v[116:117], v[116:117], v[120:121]
	v_pk_mul_f32 v[126:127], v[126:127], v[134:135] op_sel_hi:[1,0]
	v_pk_mul_f32 v[128:129], v[128:129], v[134:135] op_sel_hi:[1,0]
	v_pk_mul_f32 v[118:119], v[118:119], v[134:135] op_sel_hi:[1,0]
	v_pk_mul_f32 v[120:121], v[120:121], v[134:135] op_sel_hi:[1,0]
	v_exp_f32_e32 v126, v126
	v_exp_f32_e32 v127, v127
	v_exp_f32_e32 v128, v128
	v_exp_f32_e32 v129, v129
	v_exp_f32_e32 v118, v118
	v_exp_f32_e32 v119, v119
	v_exp_f32_e32 v120, v120
	v_exp_f32_e32 v121, v121
	v_pk_fma_f32 v[126:127], v[126:127], v[134:135], v[134:135] op_sel:[0,1,1]
	v_pk_fma_f32 v[128:129], v[128:129], v[134:135], v[134:135] op_sel:[0,1,1]
	v_pk_fma_f32 v[118:119], v[118:119], v[134:135], v[134:135] op_sel:[0,1,1]
	v_pk_fma_f32 v[120:121], v[120:121], v[134:135], v[134:135] op_sel:[0,1,1]
	v_rcp_f32_e32 v126, v126
	v_rcp_f32_e32 v127, v127
	v_rcp_f32_e32 v128, v128
	v_rcp_f32_e32 v129, v129
	v_rcp_f32_e32 v118, v118
	v_rcp_f32_e32 v119, v119
	v_rcp_f32_e32 v120, v120
	v_rcp_f32_e32 v121, v121
	v_pk_mul_f32 v[122:123], v[122:123], v[126:127]
	v_pk_mul_f32 v[124:125], v[124:125], v[128:129]
	v_pk_mul_f32 v[114:115], v[114:115], v[118:119]
	v_pk_mul_f32 v[116:117], v[116:117], v[120:121]
	v_cvt_pk_bf16_f32 v118, v122, v123
	v_cvt_pk_bf16_f32 v119, v124, v125
	v_cvt_pk_bf16_f32 v120, v114, v115
	v_cvt_pk_bf16_f32 v121, v116, v117
	v_mov_b64_e32 v[114:115], s[4:5]
	v_lshlrev_b64 v[116:117], 1, v[190:191]
	v_mad_i64_i32 v[122:123], s[4:5], v188, s9, v[114:115]
	v_lshl_add_u64 v[122:123], v[122:123], 0, v[116:117]
	global_store_dwordx4 v[122:123], v[118:121], off
	s_cmp_lg_u64 s[6:7], 0
	s_cbranch_scc0 .Lgu_nox0
	s_barrier
.Lgu_nox0:
	v_mul_f32_e32 v134, 0xbfb8aa3b, v192
	v_mul_f32_e32 v135, v192, v192
	v_rcp_f32_e32 v135, v135
	v_pk_mul_f32 v[106:107], v[106:107], v[110:111]
	v_pk_mul_f32 v[108:109], v[108:109], v[112:113]
	v_pk_mul_f32 v[98:99], v[98:99], v[102:103]
	v_pk_mul_f32 v[100:101], v[100:101], v[104:105]
	v_pk_mul_f32 v[110:111], v[110:111], v[134:135] op_sel_hi:[1,0]
	v_pk_mul_f32 v[112:113], v[112:113], v[134:135] op_sel_hi:[1,0]
	v_pk_mul_f32 v[102:103], v[102:103], v[134:135] op_sel_hi:[1,0]
	v_pk_mul_f32 v[104:105], v[104:105], v[134:135] op_sel_hi:[1,0]
	v_exp_f32_e32 v110, v110
	v_exp_f32_e32 v111, v111
	v_exp_f32_e32 v112, v112
	v_exp_f32_e32 v113, v113
	v_exp_f32_e32 v102, v102
	v_exp_f32_e32 v103, v103
	v_exp_f32_e32 v104, v104
	v_exp_f32_e32 v105, v105
	v_pk_fma_f32 v[110:111], v[110:111], v[134:135], v[134:135] op_sel:[0,1,1]
	v_pk_fma_f32 v[112:113], v[112:113], v[134:135], v[134:135] op_sel:[0,1,1]
	v_pk_fma_f32 v[102:103], v[102:103], v[134:135], v[134:135] op_sel:[0,1,1]
	v_pk_fma_f32 v[104:105], v[104:105], v[134:135], v[134:135] op_sel:[0,1,1]
	v_rcp_f32_e32 v110, v110
	v_rcp_f32_e32 v111, v111
	v_rcp_f32_e32 v112, v112
	v_rcp_f32_e32 v113, v113
	v_rcp_f32_e32 v102, v102
	v_rcp_f32_e32 v103, v103
	v_rcp_f32_e32 v104, v104
	v_rcp_f32_e32 v105, v105
	v_pk_mul_f32 v[106:107], v[106:107], v[110:111]
	v_pk_mul_f32 v[108:109], v[108:109], v[112:113]
	v_pk_mul_f32 v[98:99], v[98:99], v[102:103]
	v_pk_mul_f32 v[100:101], v[100:101], v[104:105]
	v_cvt_pk_bf16_f32 v102, v106, v107
	v_cvt_pk_bf16_f32 v103, v108, v109
	v_cvt_pk_bf16_f32 v104, v98, v99
	v_cvt_pk_bf16_f32 v105, v100, v101
	v_mad_i64_i32 v[106:107], s[4:5], v186, s9, v[114:115]
	v_lshl_add_u64 v[106:107], v[106:107], 0, v[116:117]
	global_store_dwordx4 v[106:107], v[102:105], off
	v_mul_f32_e32 v134, 0xbfb8aa3b, v148
	v_mul_f32_e32 v135, v148, v148
	v_rcp_f32_e32 v135, v135
	v_pk_mul_f32 v[90:91], v[90:91], v[94:95]
	v_pk_mul_f32 v[92:93], v[92:93], v[96:97]
	v_pk_mul_f32 v[82:83], v[82:83], v[86:87]
	v_pk_mul_f32 v[84:85], v[84:85], v[88:89]
	v_pk_mul_f32 v[94:95], v[94:95], v[134:135] op_sel_hi:[1,0]
	v_pk_mul_f32 v[96:97], v[96:97], v[134:135] op_sel_hi:[1,0]
	v_pk_mul_f32 v[86:87], v[86:87], v[134:135] op_sel_hi:[1,0]
	v_pk_mul_f32 v[88:89], v[88:89], v[134:135] op_sel_hi:[1,0]
	v_exp_f32_e32 v94, v94
	v_exp_f32_e32 v95, v95
	v_exp_f32_e32 v96, v96
	v_exp_f32_e32 v97, v97
	v_exp_f32_e32 v86, v86
	v_exp_f32_e32 v87, v87
	v_exp_f32_e32 v88, v88
	v_exp_f32_e32 v89, v89
	v_pk_fma_f32 v[94:95], v[94:95], v[134:135], v[134:135] op_sel:[0,1,1]
	v_pk_fma_f32 v[96:97], v[96:97], v[134:135], v[134:135] op_sel:[0,1,1]
	v_pk_fma_f32 v[86:87], v[86:87], v[134:135], v[134:135] op_sel:[0,1,1]
	v_pk_fma_f32 v[88:89], v[88:89], v[134:135], v[134:135] op_sel:[0,1,1]
	v_rcp_f32_e32 v94, v94
	v_rcp_f32_e32 v95, v95
	v_rcp_f32_e32 v96, v96
	v_rcp_f32_e32 v97, v97
	v_rcp_f32_e32 v86, v86
	v_rcp_f32_e32 v87, v87
	v_rcp_f32_e32 v88, v88
	v_rcp_f32_e32 v89, v89
	v_pk_mul_f32 v[90:91], v[90:91], v[94:95]
	v_pk_mul_f32 v[92:93], v[92:93], v[96:97]
	v_pk_mul_f32 v[82:83], v[82:83], v[86:87]
	v_pk_mul_f32 v[84:85], v[84:85], v[88:89]
	v_cvt_pk_bf16_f32 v86, v90, v91
	v_cvt_pk_bf16_f32 v87, v92, v93
	v_cvt_pk_bf16_f32 v88, v82, v83
	v_cvt_pk_bf16_f32 v89, v84, v85
	v_mad_i64_i32 v[90:91], s[4:5], v184, s9, v[114:115]
	v_lshl_add_u64 v[90:91], v[90:91], 0, v[116:117]
	global_store_dwordx4 v[90:91], v[86:89], off
	v_mul_f32_e32 v134, 0xbfb8aa3b, v146
	v_mul_f32_e32 v135, v146, v146
	v_rcp_f32_e32 v135, v135
	v_pk_mul_f32 v[74:75], v[74:75], v[78:79]
	v_pk_mul_f32 v[76:77], v[76:77], v[80:81]
	v_pk_mul_f32 v[66:67], v[66:67], v[70:71]
	v_pk_mul_f32 v[68:69], v[68:69], v[72:73]
	v_pk_mul_f32 v[78:79], v[78:79], v[134:135] op_sel_hi:[1,0]
	v_pk_mul_f32 v[80:81], v[80:81], v[134:135] op_sel_hi:[1,0]
	v_pk_mul_f32 v[70:71], v[70:71], v[134:135] op_sel_hi:[1,0]
	v_pk_mul_f32 v[72:73], v[72:73], v[134:135] op_sel_hi:[1,0]
	v_exp_f32_e32 v78, v78
	v_exp_f32_e32 v79, v79
	v_exp_f32_e32 v80, v80
	v_exp_f32_e32 v81, v81
	v_exp_f32_e32 v70, v70
	v_exp_f32_e32 v71, v71
	v_exp_f32_e32 v72, v72
	v_exp_f32_e32 v73, v73
	v_pk_fma_f32 v[78:79], v[78:79], v[134:135], v[134:135] op_sel:[0,1,1]
	v_pk_fma_f32 v[80:81], v[80:81], v[134:135], v[134:135] op_sel:[0,1,1]
	v_pk_fma_f32 v[70:71], v[70:71], v[134:135], v[134:135] op_sel:[0,1,1]
	v_pk_fma_f32 v[72:73], v[72:73], v[134:135], v[134:135] op_sel:[0,1,1]
	v_rcp_f32_e32 v78, v78
	v_rcp_f32_e32 v79, v79
	v_rcp_f32_e32 v80, v80
	v_rcp_f32_e32 v81, v81
	v_rcp_f32_e32 v70, v70
	v_rcp_f32_e32 v71, v71
	v_rcp_f32_e32 v72, v72
	v_rcp_f32_e32 v73, v73
	v_pk_mul_f32 v[74:75], v[74:75], v[78:79]
	v_pk_mul_f32 v[76:77], v[76:77], v[80:81]
	v_pk_mul_f32 v[66:67], v[66:67], v[70:71]
	v_pk_mul_f32 v[68:69], v[68:69], v[72:73]
	v_cvt_pk_bf16_f32 v70, v74, v75
	v_cvt_pk_bf16_f32 v71, v76, v77
	v_cvt_pk_bf16_f32 v72, v66, v67
	v_cvt_pk_bf16_f32 v73, v68, v69
	v_mad_i64_i32 v[74:75], s[4:5], v182, s9, v[114:115]
	v_lshl_add_u64 v[74:75], v[74:75], 0, v[116:117]
	global_store_dwordx4 v[74:75], v[70:73], off
	v_mul_f32_e32 v134, 0xbfb8aa3b, v140
	v_mul_f32_e32 v135, v140, v140
	v_rcp_f32_e32 v135, v135
	v_pk_mul_f32 v[58:59], v[58:59], v[62:63]
	v_pk_mul_f32 v[60:61], v[60:61], v[64:65]
	v_pk_mul_f32 v[50:51], v[50:51], v[54:55]
	v_pk_mul_f32 v[52:53], v[52:53], v[56:57]
	v_pk_mul_f32 v[62:63], v[62:63], v[134:135] op_sel_hi:[1,0]
	v_pk_mul_f32 v[64:65], v[64:65], v[134:135] op_sel_hi:[1,0]
	v_pk_mul_f32 v[54:55], v[54:55], v[134:135] op_sel_hi:[1,0]
	v_pk_mul_f32 v[56:57], v[56:57], v[134:135] op_sel_hi:[1,0]
	v_exp_f32_e32 v62, v62
	v_exp_f32_e32 v63, v63
	v_exp_f32_e32 v64, v64
	v_exp_f32_e32 v65, v65
	v_exp_f32_e32 v54, v54
	v_exp_f32_e32 v55, v55
	v_exp_f32_e32 v56, v56
	v_exp_f32_e32 v57, v57
	v_pk_fma_f32 v[62:63], v[62:63], v[134:135], v[134:135] op_sel:[0,1,1]
	v_pk_fma_f32 v[64:65], v[64:65], v[134:135], v[134:135] op_sel:[0,1,1]
	v_pk_fma_f32 v[54:55], v[54:55], v[134:135], v[134:135] op_sel:[0,1,1]
	v_pk_fma_f32 v[56:57], v[56:57], v[134:135], v[134:135] op_sel:[0,1,1]
	v_rcp_f32_e32 v62, v62
	v_rcp_f32_e32 v63, v63
	v_rcp_f32_e32 v64, v64
	v_rcp_f32_e32 v65, v65
	v_rcp_f32_e32 v54, v54
	v_rcp_f32_e32 v55, v55
	v_rcp_f32_e32 v56, v56
	v_rcp_f32_e32 v57, v57
	v_pk_mul_f32 v[58:59], v[58:59], v[62:63]
	v_pk_mul_f32 v[60:61], v[60:61], v[64:65]
	v_pk_mul_f32 v[50:51], v[50:51], v[54:55]
	v_pk_mul_f32 v[52:53], v[52:53], v[56:57]
	v_cvt_pk_bf16_f32 v54, v58, v59
	v_cvt_pk_bf16_f32 v55, v60, v61
	v_cvt_pk_bf16_f32 v56, v50, v51
	v_cvt_pk_bf16_f32 v57, v52, v53
	v_mad_i64_i32 v[58:59], s[4:5], v180, s9, v[114:115]
	v_lshl_add_u64 v[58:59], v[58:59], 0, v[116:117]
	global_store_dwordx4 v[58:59], v[54:57], off
	v_mul_f32_e32 v134, 0xbfb8aa3b, v138
	v_mul_f32_e32 v135, v138, v138
	v_rcp_f32_e32 v135, v135
	v_pk_mul_f32 v[42:43], v[42:43], v[46:47]
	v_pk_mul_f32 v[44:45], v[44:45], v[48:49]
	v_pk_mul_f32 v[34:35], v[34:35], v[38:39]
	v_pk_mul_f32 v[36:37], v[36:37], v[40:41]
	v_pk_mul_f32 v[46:47], v[46:47], v[134:135] op_sel_hi:[1,0]
	v_pk_mul_f32 v[48:49], v[48:49], v[134:135] op_sel_hi:[1,0]
	v_pk_mul_f32 v[38:39], v[38:39], v[134:135] op_sel_hi:[1,0]
	v_pk_mul_f32 v[40:41], v[40:41], v[134:135] op_sel_hi:[1,0]
	v_exp_f32_e32 v46, v46
	v_exp_f32_e32 v47, v47
	v_exp_f32_e32 v48, v48
	v_exp_f32_e32 v49, v49
	v_exp_f32_e32 v38, v38
	v_exp_f32_e32 v39, v39
	v_exp_f32_e32 v40, v40
	v_exp_f32_e32 v41, v41
	v_pk_fma_f32 v[46:47], v[46:47], v[134:135], v[134:135] op_sel:[0,1,1]
	v_pk_fma_f32 v[48:49], v[48:49], v[134:135], v[134:135] op_sel:[0,1,1]
	v_pk_fma_f32 v[38:39], v[38:39], v[134:135], v[134:135] op_sel:[0,1,1]
	v_pk_fma_f32 v[40:41], v[40:41], v[134:135], v[134:135] op_sel:[0,1,1]
	v_rcp_f32_e32 v46, v46
	v_rcp_f32_e32 v47, v47
	v_rcp_f32_e32 v48, v48
	v_rcp_f32_e32 v49, v49
	v_rcp_f32_e32 v38, v38
	v_rcp_f32_e32 v39, v39
	v_rcp_f32_e32 v40, v40
	v_rcp_f32_e32 v41, v41
	v_pk_mul_f32 v[42:43], v[42:43], v[46:47]
	v_pk_mul_f32 v[44:45], v[44:45], v[48:49]
	v_pk_mul_f32 v[34:35], v[34:35], v[38:39]
	v_pk_mul_f32 v[36:37], v[36:37], v[40:41]
	v_cvt_pk_bf16_f32 v38, v42, v43
	v_cvt_pk_bf16_f32 v39, v44, v45
	v_cvt_pk_bf16_f32 v40, v34, v35
	v_cvt_pk_bf16_f32 v41, v36, v37
	v_mad_i64_i32 v[42:43], s[4:5], v178, s9, v[114:115]
	v_lshl_add_u64 v[42:43], v[42:43], 0, v[116:117]
	global_store_dwordx4 v[42:43], v[38:41], off
	v_mul_f32_e32 v134, 0xbfb8aa3b, v132
	v_mul_f32_e32 v135, v132, v132
	v_rcp_f32_e32 v135, v135
	v_pk_mul_f32 v[26:27], v[26:27], v[30:31]
	v_pk_mul_f32 v[28:29], v[28:29], v[32:33]
	v_pk_mul_f32 v[18:19], v[18:19], v[22:23]
	v_pk_mul_f32 v[20:21], v[20:21], v[24:25]
	v_pk_mul_f32 v[30:31], v[30:31], v[134:135] op_sel_hi:[1,0]
	v_pk_mul_f32 v[32:33], v[32:33], v[134:135] op_sel_hi:[1,0]
	v_pk_mul_f32 v[22:23], v[22:23], v[134:135] op_sel_hi:[1,0]
	v_pk_mul_f32 v[24:25], v[24:25], v[134:135] op_sel_hi:[1,0]
	v_exp_f32_e32 v30, v30
	v_exp_f32_e32 v31, v31
	v_exp_f32_e32 v32, v32
	v_exp_f32_e32 v33, v33
	v_exp_f32_e32 v22, v22
	v_exp_f32_e32 v23, v23
	v_exp_f32_e32 v24, v24
	v_exp_f32_e32 v25, v25
	v_pk_fma_f32 v[30:31], v[30:31], v[134:135], v[134:135] op_sel:[0,1,1]
	v_pk_fma_f32 v[32:33], v[32:33], v[134:135], v[134:135] op_sel:[0,1,1]
	v_pk_fma_f32 v[22:23], v[22:23], v[134:135], v[134:135] op_sel:[0,1,1]
	v_pk_fma_f32 v[24:25], v[24:25], v[134:135], v[134:135] op_sel:[0,1,1]
	v_rcp_f32_e32 v30, v30
	v_rcp_f32_e32 v31, v31
	v_rcp_f32_e32 v32, v32
	v_rcp_f32_e32 v33, v33
	v_rcp_f32_e32 v22, v22
	v_rcp_f32_e32 v23, v23
	v_rcp_f32_e32 v24, v24
	v_rcp_f32_e32 v25, v25
	v_pk_mul_f32 v[26:27], v[26:27], v[30:31]
	v_pk_mul_f32 v[28:29], v[28:29], v[32:33]
	v_pk_mul_f32 v[18:19], v[18:19], v[22:23]
	v_pk_mul_f32 v[20:21], v[20:21], v[24:25]
	v_cvt_pk_bf16_f32 v22, v26, v27
	v_cvt_pk_bf16_f32 v23, v28, v29
	v_cvt_pk_bf16_f32 v24, v18, v19
	v_cvt_pk_bf16_f32 v25, v20, v21
	v_mad_i64_i32 v[26:27], s[4:5], v176, s9, v[114:115]
	v_lshl_add_u64 v[26:27], v[26:27], 0, v[116:117]
	global_store_dwordx4 v[26:27], v[22:25], off
	v_mul_f32_e32 v134, 0xbfb8aa3b, v130
	v_mul_f32_e32 v135, v130, v130
	v_rcp_f32_e32 v135, v135
	v_pk_mul_f32 v[10:11], v[10:11], v[14:15]
	v_pk_mul_f32 v[12:13], v[12:13], v[16:17]
	v_pk_mul_f32 v[2:3], v[2:3], v[6:7]
	v_pk_mul_f32 v[4:5], v[4:5], v[8:9]
	v_pk_mul_f32 v[14:15], v[14:15], v[134:135] op_sel_hi:[1,0]
	v_pk_mul_f32 v[16:17], v[16:17], v[134:135] op_sel_hi:[1,0]
	v_pk_mul_f32 v[6:7], v[6:7], v[134:135] op_sel_hi:[1,0]
	v_pk_mul_f32 v[8:9], v[8:9], v[134:135] op_sel_hi:[1,0]
	v_exp_f32_e32 v14, v14
	v_exp_f32_e32 v15, v15
	v_exp_f32_e32 v16, v16
	v_exp_f32_e32 v17, v17
	v_exp_f32_e32 v6, v6
	v_exp_f32_e32 v7, v7
	v_exp_f32_e32 v8, v8
	v_exp_f32_e32 v9, v9
	v_pk_fma_f32 v[14:15], v[14:15], v[134:135], v[134:135] op_sel:[0,1,1]
	v_pk_fma_f32 v[16:17], v[16:17], v[134:135], v[134:135] op_sel:[0,1,1]
	v_pk_fma_f32 v[6:7], v[6:7], v[134:135], v[134:135] op_sel:[0,1,1]
	v_pk_fma_f32 v[8:9], v[8:9], v[134:135], v[134:135] op_sel:[0,1,1]
	v_rcp_f32_e32 v14, v14
	v_rcp_f32_e32 v15, v15
	v_rcp_f32_e32 v16, v16
	v_rcp_f32_e32 v17, v17
	v_rcp_f32_e32 v6, v6
	v_rcp_f32_e32 v7, v7
	v_rcp_f32_e32 v8, v8
	v_rcp_f32_e32 v9, v9
	v_pk_mul_f32 v[10:11], v[10:11], v[14:15]
	v_pk_mul_f32 v[12:13], v[12:13], v[16:17]
	v_pk_mul_f32 v[2:3], v[2:3], v[6:7]
	v_pk_mul_f32 v[4:5], v[4:5], v[8:9]
	v_cvt_pk_bf16_f32 v6, v10, v11
	v_cvt_pk_bf16_f32 v7, v12, v13
	v_cvt_pk_bf16_f32 v8, v2, v3
	v_cvt_pk_bf16_f32 v9, v4, v5
	v_mad_i64_i32 v[10:11], s[4:5], v174, s9, v[114:115]
	s_andn2_b64 vcc, exec, s[0:1]
	v_lshl_add_u64 v[10:11], v[10:11], 0, v[116:117]
	s_mov_b64 s[4:5], -1
	global_store_dwordx4 v[10:11], v[6:9], off
	s_cbranch_vccnz .LBB0_1438
	s_branch .LBB0_1437
